# conversions: phase 0 keeps first-needed; ffn2(l0)+ab_out on idle SWA half (phase 7); cd_in/cd_out/w_uq/w_ukv on the 224 tile-less workgroups of the small memory-KV GEMM (phase 1)
# speedup vs baseline: 1.0060x; 1.0060x over previous
; #define LAS __attribute__((address_space(3)))
; __device__ __forceinline__ void conv_matrix(const float* W, int K, int N, const float* gain, bf16_t* WT, int Kd, int mode, int row_off, LAS float* scr, int lane, int gw, int NGW) {
;     const int nblk = N / 32, items = nblk * (K / 64);
;     for (int it = gw; it < items; it += NGW) {
;         const int kb = it / nblk, nb = it % nblk, k0 = 64 * kb, n0 = 32 * nb;
;         float wv[32];
; #pragma unroll
;         for (int i = 0; i < 32; ++i) wv[i] = W[(size_t)(k0 + 2 * i + (lane >> 5)) * N + n0 + (lane & 31)];
; __global__ void __launch_bounds__(NTHREADS, 2) hybrid_fwd(Params P) {
;     ...
;             conv_matrix(PL->in[I_CDIN], DM, CDN, PL->in[I_MIXN] + DM, (bf16_t*)(ws + WS_WCDIN), DM, 0, 0, scr, lane, gw, NGW);
.Lskip_c1:
.LBB0_109:
	s_cmp_eq_u32 s58, 7
	s_cbranch_scc1 .Lconv_return7
	s_cmpk_gt_i32 s4, 0xf1f
	s_cbranch_scc1 .LBB0_112
	v_readlane_b32 s9, v254, 8
	v_lshlrev_b32_e32 v6, 2, v54
	v_and_b32_e32 v6, 0x7c, v6
	s_waitcnt lgkmcnt(0)
	v_mov_b32_e32 v2, s9
	v_readlane_b32 s9, v254, 11
	ds_read_b64 v[2:3], v2
	v_mov_b32_e32 v7, v0
	v_mov_b32_e32 v4, s9
	ds_read_b64 v[4:5], v4
	v_add_u32_e32 v8, s5, v6
	s_waitcnt vmcnt(0)
	v_lshrrev_b32_e32 v17, 3, v1
	v_lshrrev_b32_e32 v16, 5, v1
	s_mov_b64 s[18:19], 0x2000
	s_waitcnt lgkmcnt(0)
	v_lshl_add_u64 v[4:5], v[4:5], 0, v[6:7]
	v_lshlrev_b32_e32 v6, 3, v1
	v_and_b32_e32 v6, 56, v6
	v_mul_u32_u24_e32 v9, 0x84, v6
	v_lshlrev_b32_e32 v6, 1, v6
	v_lshlrev_b32_e32 v10, 2, v17
	v_lshl_add_u64 v[2:3], v[2:3], 0, s[18:19]
	v_lshl_add_u64 v[6:7], s[0:1], 0, v[6:7]
	s_mov_b64 s[18:19], 0xb500000
	v_add3_u32 v18, s5, v9, v10
	v_mul_u32_u24_e32 v9, 0x84, v16
	v_lshl_add_u64 v[6:7], v[6:7], 0, s[18:19]
	s_lshl_b32 s9, s4, 5
	s_lshl_b32 s12, s8, 5
	v_add_u32_e32 v19, v8, v9
	s_mov_b32 s18, s4
	s_cmp_lg_u32 s58, 1
	s_cbranch_scc1 .Lskip_c2

; #define LAS __attribute__((address_space(3)))
; __device__ __forceinline__ void conv_matrix(const float* W, int K, int N, const float* gain, bf16_t* WT, int Kd, int mode, int row_off, LAS float* scr, int lane, int gw, int NGW) {
;     const int nblk = N / 32, items = nblk * (K / 64);
;     for (int it = gw; it < items; it += NGW) {
;         const int kb = it / nblk, nb = it % nblk, k0 = 64 * kb, n0 = 32 * nb;
;         float wv[32];
; #pragma unroll
;         for (int i = 0; i < 32; ++i) wv[i] = W[(size_t)(k0 + 2 * i + (lane >> 5)) * N + n0 + (lane & 31)];
; __global__ void __launch_bounds__(NTHREADS, 2) hybrid_fwd(Params P) {
;     ...
;             conv_matrix(PL->in[I_CDOUT], DM, DM, nullptr, (bf16_t*)(ws + WS_WCDOUT), DM, 0, 0, scr, lane, gw, NGW);
.Lskip_c2:
.LBB0_112:
	s_waitcnt lgkmcnt(0)
	v_cndmask_b32_e64 v2, 0, 1, s[16:17]
	v_cmp_ne_u32_e64 s[38:39], 1, v2
	s_andn2_b64 vcc, exec, s[16:17]
	s_cbranch_vccnz .LBB0_115
	v_readlane_b32 s9, v254, 12
	v_lshlrev_b32_e32 v4, 2, v54
	v_mov_b32_e32 v5, v0
	v_mov_b32_e32 v2, s9
	ds_read_b64 v[2:3], v2
	v_and_b32_e32 v4, 0x7c, v4
	v_add_u32_e32 v9, s5, v4
	v_lshrrev_b32_e32 v7, 3, v1
	v_lshrrev_b32_e32 v6, 5, v1
	s_waitcnt lgkmcnt(0)
	v_lshl_add_u64 v[2:3], v[2:3], 0, v[4:5]
	v_lshlrev_b32_e32 v4, 3, v1
	v_and_b32_e32 v4, 56, v4
	v_mul_u32_u24_e32 v8, 0x84, v4
	v_lshlrev_b32_e32 v4, 1, v4
	v_lshlrev_b32_e32 v10, 2, v7
	v_lshl_add_u64 v[4:5], s[0:1], 0, v[4:5]
	s_mov_b64 s[16:17], 0xc500000
	v_add3_u32 v8, s5, v8, v10
	v_mul_u32_u24_e32 v10, 0x84, v6
	v_lshl_add_u64 v[4:5], v[4:5], 0, s[16:17]
	s_lshl_b32 s9, s4, 5
	s_lshl_b32 s12, s8, 5
	v_add_u32_e32 v9, v9, v10
	s_mov_b32 s22, s4
	s_cmp_lg_u32 s58, 1
	s_cbranch_scc1 .Lskip_c3

; #define LAS __attribute__((address_space(3)))
; __device__ __forceinline__ void conv_matrix(const float* W, int K, int N, const float* gain, bf16_t* WT, int Kd, int mode, int row_off, LAS float* scr, int lane, int gw, int NGW) {
;     const int nblk = N / 32, items = nblk * (K / 64);
;     for (int it = gw; it < items; it += NGW) {
;         const int kb = it / nblk, nb = it % nblk, k0 = 64 * kb, n0 = 32 * nb;
;         float wv[32];
; #pragma unroll
;         for (int i = 0; i < 32; ++i) wv[i] = W[(size_t)(k0 + 2 * i + (lane >> 5)) * N + n0 + (lane & 31)];
; __global__ void __launch_bounds__(NTHREADS, 2) hybrid_fwd(Params P) {
;     ...
;             conv_matrix(PL->in[I_WUQ], 512, 1536, PL->in[I_CQN], (bf16_t*)(ws + WS_WUQ), 512, 0, 0, scr, lane, gw, NGW);
.Lskip_c3:
.LBB0_115:
	s_cmpk_gt_i32 s4, 0x17f
	s_cbranch_scc1 .LBB0_120
	v_readlane_b32 s9, v254, 13
	v_lshlrev_b32_e32 v6, 2, v54
	v_and_b32_e32 v6, 0x7c, v6
	v_mov_b32_e32 v2, s9
	v_readlane_b32 s9, v254, 14
	v_mov_b32_e32 v7, v0
	v_add_u32_e32 v8, s5, v6
	v_mov_b32_e32 v4, s9
	ds_read_b64 v[2:3], v2
	ds_read_b64 v[4:5], v4
	v_lshrrev_b32_e32 v44, 3, v1
	v_lshrrev_b32_e32 v35, 5, v1
	v_lshlrev_b32_e32 v10, 2, v44
	s_mov_b64 s[16:17], 0xcd00000
	s_waitcnt lgkmcnt(0)
	v_lshl_add_u64 v[4:5], v[4:5], 0, v[6:7]
	v_lshlrev_b32_e32 v6, 3, v1
	v_and_b32_e32 v6, 56, v6
	v_mul_u32_u24_e32 v9, 0x84, v6
	v_lshlrev_b32_e32 v6, 1, v6
	v_lshl_add_u64 v[6:7], s[0:1], 0, v[6:7]
	v_add3_u32 v45, s5, v9, v10
	v_mul_u32_u24_e32 v9, 0x84, v35
	v_cmp_ne_u64_e64 s[40:41], 0, v[2:3]
	v_lshl_add_u64 v[6:7], v[6:7], 0, s[16:17]
	s_lshl_b32 s9, s4, 5
	s_lshl_b32 s12, s8, 5
	v_add_u32_e32 v46, v8, v9
	s_mov_b32 s22, s4
	s_cmp_lg_u32 s58, 1
	s_cbranch_scc1 .LBB0_120
	s_branch .LBB0_118

; #define LAS __attribute__((address_space(3)))
; __device__ __forceinline__ void conv_matrix(const float* W, int K, int N, const float* gain, bf16_t* WT, int Kd, int mode, int row_off, LAS float* scr, int lane, int gw, int NGW) {
;     const int nblk = N / 32, items = nblk * (K / 64);
;     for (int it = gw; it < items; it += NGW) {
;         const int kb = it / nblk, nb = it % nblk, k0 = 64 * kb, n0 = 32 * nb;
;         float wv[32];
; #pragma unroll
;         for (int i = 0; i < 32; ++i) wv[i] = W[(size_t)(k0 + 2 * i + (lane >> 5)) * N + n0 + (lane & 31)];
; __global__ void __launch_bounds__(NTHREADS, 2) hybrid_fwd(Params P) {
;     ...
;             conv_matrix(PL->in[I_WUKV], 256, 2048, PL->in[I_CKVN], (bf16_t*)(ws + WS_WUKV), 256, 0, 0, scr, lane, gw, NGW);
.LBB0_122:
	s_andn2_b64 vcc, exec, s[16:17]
	s_cbranch_vccnz .LBB0_127
	v_readlane_b32 s9, v254, 15
	v_mov_b32_e32 v11, v0
	v_lshrrev_b32_e32 v35, 5, v1
	v_mov_b32_e32 v2, s9
	v_readlane_b32 s9, v254, 16
	v_lshrrev_b32_e32 v52, 3, v1
	s_mov_b64 s[16:17], 0xcf00000
	v_mov_b32_e32 v3, s9
	ds_read_b64 v[6:7], v2
	ds_read_b64 v[4:5], v3
	v_and_b32_e32 v2, 31, v54
	v_lshlrev_b32_e32 v10, 2, v2
	v_add_u32_e32 v12, s5, v10
	v_lshlrev_b32_e32 v13, 2, v52
	s_waitcnt lgkmcnt(0)
	v_lshl_add_u64 v[8:9], v[4:5], 0, v[10:11]
	v_lshlrev_b32_e32 v4, 3, v1
	v_and_b32_e32 v4, 56, v4
	v_lshlrev_b32_e32 v10, 1, v4
	v_mul_u32_u24_e32 v48, 0x84, v4
	v_lshl_add_u64 v[10:11], s[0:1], 0, v[10:11]
	v_mul_u32_u24_e32 v49, 0x84, v35
	v_mov_b32_e32 v3, v0
	v_cmp_ne_u64_e64 s[40:41], 0, v[6:7]
	v_mov_b32_e32 v5, v0
	v_lshl_add_u64 v[10:11], v[10:11], 0, s[16:17]
	v_add3_u32 v50, s5, v48, v13
	v_or_b32_e32 v53, 8, v52
	v_or_b32_e32 v55, 16, v52
	v_or_b32_e32 v56, 24, v52
	s_lshl_b32 s9, s4, 5
	s_lshl_b32 s12, s8, 5
	v_add_u32_e32 v51, v12, v49
	s_mov_b32 s18, s4
	s_cmp_lg_u32 s58, 1
	s_cbranch_scc1 .LBB0_127
	s_branch .LBB0_125

; #define LAS __attribute__((address_space(3)))
; __device__ __forceinline__ void conv_matrix(const float* W, int K, int N, const float* gain, bf16_t* WT, int Kd, int mode, int row_off, LAS float* scr, int lane, int gw, int NGW) {
;     const int nblk = N / 32, items = nblk * (K / 64);
;     for (int it = gw; it < items; it += NGW) {
;         const int kb = it / nblk, nb = it % nblk, k0 = 64 * kb, n0 = 32 * nb;
;         float wv[32];
; #pragma unroll
;         for (int i = 0; i < 32; ++i) wv[i] = W[(size_t)(k0 + 2 * i + (lane >> 5)) * N + n0 + (lane & 31)];
; __global__ void __launch_bounds__(NTHREADS, 2) hybrid_fwd(Params P) {
;     ...
;             for (int l2 = 0; l2 < 2; ++l2) {
;                 conv_matrix(PL->in[I_MXWQ] + (size_t)l2 * DM * 512, DM, 512, PL->in[I_MXN] + l2 * DM, (bf16_t*)(ws + WS_WMQ) + (size_t)l2 * 512 * DM, DM, 0, 0, scr, lane, gw, NGW);
;                 conv_matrix(PL->in[I_MXWO] + (size_t)l2 * 512 * DM, 512, DM, nullptr, (bf16_t*)(ws + WS_WMO) + (size_t)l2 * DM * 512, 512, 0, 0, scr, lane, gw, NGW);
.LBB0_127:
	s_cmp_eq_u32 s58, 1
	s_cbranch_scc1 .Lconv_return9
	v_lshl_add_u64 v[4:5], v[4:5], 1, s[0:1]
	s_mov_b64 s[18:19], 0xd000000
	s_cmpk_lt_i32 s4, 0x200
	v_lshlrev_b32_e32 v8, 2, v2
	v_add_u32_e32 v9, s5, v48
	v_lshl_add_u64 v[6:7], v[4:5], 0, s[18:19]
	s_mov_b64 s[18:19], 0xd400000
	s_cselect_b64 s[16:17], -1, 0
	v_lshl_add_u32 v57, v52, 2, v9
	v_add3_u32 v58, s5, v8, v49
	v_lshl_add_u32 v59, v53, 2, v9
	v_lshl_add_u32 v60, v55, 2, v9
	v_lshl_add_u32 v61, v56, 2, v9
	v_lshl_add_u64 v[8:9], v[4:5], 0, s[18:19]
	s_mov_b32 s5, 0
	s_mov_b64 s[18:19], -1
	s_branch .LBB0_129

; __global__ void __launch_bounds__(NTHREADS, 2) hybrid_fwd(Params P) {
;     ...
;             pg8::StaticOrder S; S.init(g.M, g.N, G, bx);
;             pg8::gemm_phase<pg8::EpiAny, pg8::StaticOrder, true, true>(lds, g, S, E, tid);
;         }
;         if (EN(6) && ph == 5) { ROOTS
.LBB0_428:
	s_cmp_eq_u32 s58, 1
	s_cbranch_scc0 .Lno_idle_conv
	s_movk_i32 s10, 32
	s_cmp_ge_u32 s73, s10
	s_cbranch_scc0 .Lno_idle_conv
	v_mov_b32_e32 v54, v236
	s_sub_i32 s12, s73, s10
	s_sub_i32 s10, s56, s10
	s_mov_b64 s[0:1], s[30:31]
	s_movk_i32 s3, 0x5800
	s_movk_i32 s89, 0x3c80
	s_movk_i32 s91, 0x1800
	v_readfirstlane_b32 s22, v54
	s_branch .Lconv_entry
